# nt hint on the never-re-read f32 K/V cache output stores of the attention kernels (k2 own-diagonal, k9 band shift)
# speedup vs baseline: 1.0376x; 1.0096x over previous
.LBB2_32:
	s_cmp_lg_u64 s[82:83], 0
	s_cselect_b64 s[72:73], -1, 0
	s_cmp_eq_u32 s75, 0
	s_cselect_b64 s[12:13], -1, 0
	s_and_b64 s[12:13], s[72:73], s[12:13]
	s_andn2_b64 vcc, exec, s[12:13]
	v_ashrrev_i32_e32 v3, 31, v2
	s_cbranch_vccnz .LBB2_34
	v_lshlrev_b64 v[4:5], 11, v[2:3]
	v_lshl_or_b32 v4, v9, 5, v4
	s_waitcnt vmcnt(3)
	v_lshlrev_b32_e32 v12, 16, v82
	v_and_b32_e32 v13, 0xffff0000, v82
	v_lshlrev_b32_e32 v14, 16, v83
	v_and_b32_e32 v15, 0xffff0000, v83
	v_lshl_add_u64 v[16:17], s[82:83], 0, v[4:5]
	global_store_dwordx4 v[16:17], v[12:15], off nt
	s_mov_b64 s[12:13], 0x10000
	s_mov_b32 s14, 0x10000
	v_lshlrev_b32_e32 v12, 16, v84
	v_and_b32_e32 v13, 0xffff0000, v84
	v_lshlrev_b32_e32 v14, 16, v85
	v_and_b32_e32 v15, 0xffff0000, v85
	global_store_dwordx4 v[16:17], v[12:15], off offset:16 nt
	v_lshl_add_u64 v[18:19], v[16:17], 0, s[12:13]
	v_add_co_u32_e32 v16, vcc, s14, v16
	s_waitcnt vmcnt(4)
	v_lshlrev_b32_e32 v12, 16, v86
	v_and_b32_e32 v13, 0xffff0000, v86
	v_lshlrev_b32_e32 v14, 16, v87
	v_and_b32_e32 v15, 0xffff0000, v87
	v_addc_co_u32_e32 v17, vcc, 0, v17, vcc
	global_store_dwordx4 v[16:17], v[12:15], off nt
	v_lshl_add_u64 v[4:5], s[70:71], 0, v[4:5]
	v_lshl_add_u64 v[16:17], v[4:5], 0, s[12:13]
	v_lshlrev_b32_e32 v12, 16, v88
	v_and_b32_e32 v13, 0xffff0000, v88
	v_lshlrev_b32_e32 v14, 16, v89
	v_and_b32_e32 v15, 0xffff0000, v89
	global_store_dwordx4 v[18:19], v[12:15], off offset:16 nt
	s_waitcnt vmcnt(5)
	s_nop 0
	v_lshlrev_b32_e32 v12, 16, v90
	v_and_b32_e32 v13, 0xffff0000, v90
	v_lshlrev_b32_e32 v14, 16, v91
	v_and_b32_e32 v15, 0xffff0000, v91
	global_store_dwordx4 v[4:5], v[12:15], off nt
	s_nop 1
	v_lshlrev_b32_e32 v12, 16, v92
	v_and_b32_e32 v13, 0xffff0000, v92
	v_lshlrev_b32_e32 v14, 16, v93
	v_and_b32_e32 v15, 0xffff0000, v93
	global_store_dwordx4 v[4:5], v[12:15], off offset:16 nt
	v_add_co_u32_e32 v4, vcc, 0x10000, v4
	s_waitcnt vmcnt(6)
	v_lshlrev_b32_e32 v12, 16, v94
	v_and_b32_e32 v13, 0xffff0000, v94
	v_lshlrev_b32_e32 v14, 16, v95
	v_and_b32_e32 v15, 0xffff0000, v95
	v_addc_co_u32_e32 v5, vcc, 0, v5, vcc
	global_store_dwordx4 v[4:5], v[12:15], off nt
	s_nop 1
	v_lshlrev_b32_e32 v12, 16, v96
	v_and_b32_e32 v13, 0xffff0000, v96
	v_lshlrev_b32_e32 v14, 16, v97
	v_and_b32_e32 v15, 0xffff0000, v97
	global_store_dwordx4 v[16:17], v[12:15], off offset:16 nt

.LBB2_61:
	s_add_i32 s0, s89, s94
	s_cmp_eq_u32 s0, 3
	s_cselect_b64 s[0:1], -1, 0
	s_and_b64 s[0:1], s[72:73], s[0:1]
	s_andn2_b64 vcc, exec, s[0:1]
	s_cbranch_vccnz .LBB2_63
	v_lshl_add_u64 v[38:39], v[164:165], 0, v[142:143]
	v_add_co_u32_e32 v40, vcc, 0x20000, v38
	s_waitcnt vmcnt(3)
	v_lshlrev_b32_e32 v34, 16, v82
	v_and_b32_e32 v35, 0xffff0000, v82
	v_lshlrev_b32_e32 v36, 16, v83
	v_and_b32_e32 v37, 0xffff0000, v83
	v_addc_co_u32_e32 v41, vcc, 0, v39, vcc
	s_mov_b32 s0, 0x30000
	global_store_dwordx4 v[40:41], v[34:37], off nt
	v_add_co_u32_e32 v38, vcc, s0, v38
	s_nop 0
	v_lshlrev_b32_e32 v34, 16, v84
	v_and_b32_e32 v35, 0xffff0000, v84
	v_lshlrev_b32_e32 v36, 16, v85
	v_and_b32_e32 v37, 0xffff0000, v85
	global_store_dwordx4 v[40:41], v[34:37], off offset:16 nt
	v_addc_co_u32_e32 v39, vcc, 0, v39, vcc
	s_waitcnt vmcnt(4)
	v_lshlrev_b32_e32 v34, 16, v86
	v_and_b32_e32 v35, 0xffff0000, v86
	v_lshlrev_b32_e32 v36, 16, v87
	v_and_b32_e32 v37, 0xffff0000, v87
	global_store_dwordx4 v[38:39], v[34:37], off nt
	s_mov_b32 s0, 0x20000
	s_nop 0
	v_lshlrev_b32_e32 v34, 16, v88
	v_and_b32_e32 v35, 0xffff0000, v88
	v_lshlrev_b32_e32 v36, 16, v89
	v_and_b32_e32 v37, 0xffff0000, v89
	global_store_dwordx4 v[38:39], v[34:37], off offset:16 nt
	v_lshl_add_u64 v[38:39], v[148:149], 0, v[142:143]
	v_add_co_u32_e32 v40, vcc, s0, v38
	s_waitcnt vmcnt(5)
	v_lshlrev_b32_e32 v34, 16, v90
	v_and_b32_e32 v35, 0xffff0000, v90
	v_lshlrev_b32_e32 v36, 16, v91
	v_and_b32_e32 v37, 0xffff0000, v91
	v_addc_co_u32_e32 v41, vcc, 0, v39, vcc
	global_store_dwordx4 v[40:41], v[34:37], off nt
	v_add_co_u32_e32 v38, vcc, 0x30000, v38
	s_nop 0
	v_lshlrev_b32_e32 v34, 16, v92
	v_and_b32_e32 v35, 0xffff0000, v92
	v_lshlrev_b32_e32 v36, 16, v93
	v_and_b32_e32 v37, 0xffff0000, v93
	global_store_dwordx4 v[40:41], v[34:37], off offset:16 nt
	v_addc_co_u32_e32 v39, vcc, 0, v39, vcc
	s_waitcnt vmcnt(6)
	v_lshlrev_b32_e32 v34, 16, v94
	v_and_b32_e32 v35, 0xffff0000, v94
	v_lshlrev_b32_e32 v36, 16, v95
	v_and_b32_e32 v37, 0xffff0000, v95
	global_store_dwordx4 v[38:39], v[34:37], off nt
	s_nop 1
	v_lshlrev_b32_e32 v34, 16, v96
	v_and_b32_e32 v35, 0xffff0000, v96
	v_lshlrev_b32_e32 v36, 16, v97
	v_and_b32_e32 v37, 0xffff0000, v97
	global_store_dwordx4 v[38:39], v[34:37], off offset:16 nt
	s_nop 1
	v_add_u32_e32 v34, v132, v128
	ds_write_b128 v34, v[82:85] offset:17408
	ds_write_b128 v34, v[86:89] offset:26112
	ds_write_b128 v133, v[90:93]
	ds_write_b128 v133, v[94:97] offset:10240
	s_and_saveexec_b64 s[0:1], s[4:5]
	ds_write_b32 v179, v127
	s_or_b64 exec, exec, s[0:1]
	s_branch .LBB2_66

.LBB2_87:
	s_add_i32 s0, s91, s94
	s_cmp_eq_u32 s0, 3
	s_cselect_b64 s[0:1], -1, 0
	s_and_b64 s[0:1], s[72:73], s[0:1]
	s_andn2_b64 vcc, exec, s[0:1]
	s_cbranch_vccnz .LBB2_89
	s_waitcnt vmcnt(3)
	v_lshlrev_b32_e32 v34, 16, v102
	v_and_b32_e32 v35, 0xffff0000, v102
	v_lshlrev_b32_e32 v36, 16, v103
	v_and_b32_e32 v37, 0xffff0000, v103
	global_store_dwordx4 v[138:139], v[34:37], off nt
	s_nop 1
	v_lshlrev_b32_e32 v34, 16, v104
	v_and_b32_e32 v35, 0xffff0000, v104
	v_lshlrev_b32_e32 v36, 16, v105
	v_and_b32_e32 v37, 0xffff0000, v105
	global_store_dwordx4 v[138:139], v[34:37], off offset:16 nt
	s_waitcnt vmcnt(4)
	s_nop 0
	v_lshlrev_b32_e32 v34, 16, v106
	v_and_b32_e32 v35, 0xffff0000, v106
	v_lshlrev_b32_e32 v36, 16, v107
	v_and_b32_e32 v37, 0xffff0000, v107
	global_store_dwordx4 v[140:141], v[34:37], off nt
	s_nop 1
	v_lshlrev_b32_e32 v34, 16, v108
	v_and_b32_e32 v35, 0xffff0000, v108
	v_lshlrev_b32_e32 v36, 16, v109
	v_and_b32_e32 v37, 0xffff0000, v109
	global_store_dwordx4 v[140:141], v[34:37], off offset:16 nt
	s_waitcnt vmcnt(5)
	s_nop 0
	v_lshlrev_b32_e32 v34, 16, v110
	v_and_b32_e32 v35, 0xffff0000, v110
	v_lshlrev_b32_e32 v36, 16, v111
	v_and_b32_e32 v37, 0xffff0000, v111
	global_store_dwordx4 v[134:135], v[34:37], off nt
	s_nop 1
	v_lshlrev_b32_e32 v34, 16, v112
	v_and_b32_e32 v35, 0xffff0000, v112
	v_lshlrev_b32_e32 v36, 16, v113
	v_and_b32_e32 v37, 0xffff0000, v113
	global_store_dwordx4 v[134:135], v[34:37], off offset:16 nt
	s_waitcnt vmcnt(6)
	s_nop 0
	v_lshlrev_b32_e32 v34, 16, v114
	v_and_b32_e32 v35, 0xffff0000, v114
	v_lshlrev_b32_e32 v36, 16, v115
	v_and_b32_e32 v37, 0xffff0000, v115
	global_store_dwordx4 v[136:137], v[34:37], off nt
	s_nop 1
	v_lshlrev_b32_e32 v34, 16, v116
	v_and_b32_e32 v35, 0xffff0000, v116
	v_lshlrev_b32_e32 v36, 16, v117
	v_and_b32_e32 v37, 0xffff0000, v117
	global_store_dwordx4 v[136:137], v[34:37], off offset:16 nt
	ds_write_b128 v131, v[102:105]
	ds_write_b128 v131, v[106:109] offset:8704
	ds_write_b128 v174, v[110:113] offset:34816
	ds_write_b128 v174, v[114:117] offset:45056
	s_and_saveexec_b64 s[0:1], s[4:5]
	ds_write_b32 v182, v184
	s_or_b64 exec, exec, s[0:1]
	s_branch .LBB2_92

.LBB2_115:
	s_cmp_lg_u64 s[20:21], 0
	s_cselect_b64 s[6:7], -1, 0
	s_cmp_eq_u32 s13, 0
	s_cselect_b64 s[22:23], -1, 0
	s_and_b64 s[22:23], s[6:7], s[22:23]
	s_andn2_b64 vcc, exec, s[22:23]
	v_ashrrev_i32_e32 v19, 31, v18
	s_cbranch_vccnz .LBB2_117
	v_lshlrev_b64 v[28:29], 11, v[18:19]
	v_lshl_or_b32 v28, v23, 5, v28
	s_waitcnt vmcnt(3)
	v_lshlrev_b32_e32 v24, 16, v2
	v_and_b32_e32 v25, 0xffff0000, v2
	v_lshlrev_b32_e32 v26, 16, v3
	v_and_b32_e32 v27, 0xffff0000, v3
	v_lshl_add_u64 v[30:31], s[20:21], 0, v[28:29]
	global_store_dwordx4 v[30:31], v[24:27], off nt
	s_mov_b64 s[22:23], 0x10000
	s_mov_b32 s31, 0x10000
	v_lshlrev_b32_e32 v24, 16, v4
	v_and_b32_e32 v25, 0xffff0000, v4
	v_lshlrev_b32_e32 v26, 16, v5
	v_and_b32_e32 v27, 0xffff0000, v5
	global_store_dwordx4 v[30:31], v[24:27], off offset:16 nt
	v_lshl_add_u64 v[32:33], v[30:31], 0, s[22:23]
	v_add_co_u32_e32 v30, vcc, s31, v30
	s_waitcnt vmcnt(4)
	v_lshlrev_b32_e32 v24, 16, v6
	v_and_b32_e32 v25, 0xffff0000, v6
	v_lshlrev_b32_e32 v26, 16, v7
	v_and_b32_e32 v27, 0xffff0000, v7
	v_addc_co_u32_e32 v31, vcc, 0, v31, vcc
	global_store_dwordx4 v[30:31], v[24:27], off nt
	v_lshl_add_u64 v[28:29], s[8:9], 0, v[28:29]
	v_lshl_add_u64 v[30:31], v[28:29], 0, s[22:23]
	v_lshlrev_b32_e32 v24, 16, v8
	v_and_b32_e32 v25, 0xffff0000, v8
	v_lshlrev_b32_e32 v26, 16, v9
	v_and_b32_e32 v27, 0xffff0000, v9
	global_store_dwordx4 v[32:33], v[24:27], off offset:16 nt
	s_waitcnt vmcnt(5)
	s_nop 0
	v_lshlrev_b32_e32 v24, 16, v10
	v_and_b32_e32 v25, 0xffff0000, v10
	v_lshlrev_b32_e32 v26, 16, v11
	v_and_b32_e32 v27, 0xffff0000, v11
	global_store_dwordx4 v[28:29], v[24:27], off nt
	s_nop 1
	v_lshlrev_b32_e32 v24, 16, v12
	v_and_b32_e32 v25, 0xffff0000, v12
	v_lshlrev_b32_e32 v26, 16, v13
	v_and_b32_e32 v27, 0xffff0000, v13
	global_store_dwordx4 v[28:29], v[24:27], off offset:16 nt
	v_add_co_u32_e32 v28, vcc, 0x10000, v28
	s_waitcnt vmcnt(6)
	v_lshlrev_b32_e32 v24, 16, v14
	v_and_b32_e32 v25, 0xffff0000, v14
	v_lshlrev_b32_e32 v26, 16, v15
	v_and_b32_e32 v27, 0xffff0000, v15
	v_addc_co_u32_e32 v29, vcc, 0, v29, vcc
	global_store_dwordx4 v[28:29], v[24:27], off nt
	s_nop 1
	v_lshlrev_b32_e32 v24, 16, v16
	v_and_b32_e32 v25, 0xffff0000, v16
	v_lshlrev_b32_e32 v26, 16, v17
	v_and_b32_e32 v27, 0xffff0000, v17
	global_store_dwordx4 v[30:31], v[24:27], off offset:16 nt

.LBB2_141:
	s_add_i32 s0, s22, s19
	s_cmp_eq_u32 s0, 3
	s_cselect_b64 s[0:1], -1, 0
	s_and_b64 s[0:1], s[6:7], s[0:1]
	s_andn2_b64 vcc, exec, s[0:1]
	s_cbranch_vccnz .LBB2_143
	v_lshl_add_u64 v[70:71], v[222:223], 0, v[202:203]
	v_add_co_u32_e32 v72, vcc, 0x20000, v70
	s_waitcnt vmcnt(3)
	v_lshlrev_b32_e32 v66, 16, v118
	v_and_b32_e32 v67, 0xffff0000, v118
	v_lshlrev_b32_e32 v68, 16, v119
	v_and_b32_e32 v69, 0xffff0000, v119
	v_addc_co_u32_e32 v73, vcc, 0, v71, vcc
	s_mov_b32 s0, 0x30000
	global_store_dwordx4 v[72:73], v[66:69], off nt
	v_add_co_u32_e32 v70, vcc, s0, v70
	s_nop 0
	v_lshlrev_b32_e32 v66, 16, v120
	v_and_b32_e32 v67, 0xffff0000, v120
	v_lshlrev_b32_e32 v68, 16, v121
	v_and_b32_e32 v69, 0xffff0000, v121
	global_store_dwordx4 v[72:73], v[66:69], off offset:16 nt
	v_addc_co_u32_e32 v71, vcc, 0, v71, vcc
	s_waitcnt vmcnt(4)
	v_lshlrev_b32_e32 v66, 16, v122
	v_and_b32_e32 v67, 0xffff0000, v122
	v_lshlrev_b32_e32 v68, 16, v123
	v_and_b32_e32 v69, 0xffff0000, v123
	global_store_dwordx4 v[70:71], v[66:69], off nt
	s_mov_b32 s0, 0x20000
	s_nop 0
	v_lshlrev_b32_e32 v66, 16, v124
	v_and_b32_e32 v67, 0xffff0000, v124
	v_lshlrev_b32_e32 v68, 16, v125
	v_and_b32_e32 v69, 0xffff0000, v125
	global_store_dwordx4 v[70:71], v[66:69], off offset:16 nt
	v_lshl_add_u64 v[70:71], v[220:221], 0, v[202:203]
	v_add_co_u32_e32 v72, vcc, s0, v70
	s_waitcnt vmcnt(5)
	v_lshlrev_b32_e32 v66, 16, v126
	v_and_b32_e32 v67, 0xffff0000, v126
	v_lshlrev_b32_e32 v68, 16, v127
	v_and_b32_e32 v69, 0xffff0000, v127
	v_addc_co_u32_e32 v73, vcc, 0, v71, vcc
	global_store_dwordx4 v[72:73], v[66:69], off nt
	v_add_co_u32_e32 v70, vcc, 0x30000, v70
	s_nop 0
	v_lshlrev_b32_e32 v66, 16, v128
	v_and_b32_e32 v67, 0xffff0000, v128
	v_lshlrev_b32_e32 v68, 16, v129
	v_and_b32_e32 v69, 0xffff0000, v129
	global_store_dwordx4 v[72:73], v[66:69], off offset:16 nt
	v_addc_co_u32_e32 v71, vcc, 0, v71, vcc
	s_waitcnt vmcnt(6)
	v_lshlrev_b32_e32 v66, 16, v130
	v_and_b32_e32 v67, 0xffff0000, v130
	v_lshlrev_b32_e32 v68, 16, v131
	v_and_b32_e32 v69, 0xffff0000, v131
	global_store_dwordx4 v[70:71], v[66:69], off nt
	s_nop 1
	v_lshlrev_b32_e32 v66, 16, v132
	v_and_b32_e32 v67, 0xffff0000, v132
	v_lshlrev_b32_e32 v68, 16, v133
	v_and_b32_e32 v69, 0xffff0000, v133
	global_store_dwordx4 v[70:71], v[66:69], off offset:16 nt
	s_nop 1
	v_add_u32_e32 v66, v188, v243
	ds_write_b128 v66, v[118:121] offset:17408
	ds_write_b128 v66, v[122:125] offset:26112
	ds_write_b128 v189, v[126:129]
	ds_write_b128 v189, v[130:133] offset:10240
	s_branch .LBB2_144

.LBB2_163:
	s_add_i32 s0, s16, s19
	s_cmp_eq_u32 s0, 3
	s_cselect_b64 s[0:1], -1, 0
	s_and_b64 s[0:1], s[6:7], s[0:1]
	s_andn2_b64 vcc, exec, s[0:1]
	s_cbranch_vccnz .LBB2_165
	s_waitcnt vmcnt(3)
	v_lshlrev_b32_e32 v66, 16, v134
	v_and_b32_e32 v67, 0xffff0000, v134
	v_lshlrev_b32_e32 v68, 16, v135
	v_and_b32_e32 v69, 0xffff0000, v135
	global_store_dwordx4 v[190:191], v[66:69], off nt
	s_nop 1
	v_lshlrev_b32_e32 v66, 16, v136
	v_and_b32_e32 v67, 0xffff0000, v136
	v_lshlrev_b32_e32 v68, 16, v137
	v_and_b32_e32 v69, 0xffff0000, v137
	global_store_dwordx4 v[190:191], v[66:69], off offset:16 nt
	s_waitcnt vmcnt(4)
	s_nop 0
	v_lshlrev_b32_e32 v66, 16, v138
	v_and_b32_e32 v67, 0xffff0000, v138
	v_lshlrev_b32_e32 v68, 16, v139
	v_and_b32_e32 v69, 0xffff0000, v139
	global_store_dwordx4 v[232:233], v[66:69], off nt
	s_nop 1
	v_lshlrev_b32_e32 v66, 16, v140
	v_and_b32_e32 v67, 0xffff0000, v140
	v_lshlrev_b32_e32 v68, 16, v141
	v_and_b32_e32 v69, 0xffff0000, v141
	global_store_dwordx4 v[232:233], v[66:69], off offset:16 nt
	s_waitcnt vmcnt(5)
	s_nop 0
	v_lshlrev_b32_e32 v66, 16, v142
	v_and_b32_e32 v67, 0xffff0000, v142
	v_lshlrev_b32_e32 v68, 16, v143
	v_and_b32_e32 v69, 0xffff0000, v143
	global_store_dwordx4 v[192:193], v[66:69], off nt
	s_nop 1
	v_lshlrev_b32_e32 v66, 16, v144
	v_and_b32_e32 v67, 0xffff0000, v144
	v_lshlrev_b32_e32 v68, 16, v145
	v_and_b32_e32 v69, 0xffff0000, v145
	global_store_dwordx4 v[192:193], v[66:69], off offset:16 nt
	s_waitcnt vmcnt(6)
	s_nop 0
	v_lshlrev_b32_e32 v66, 16, v146
	v_and_b32_e32 v67, 0xffff0000, v146
	v_lshlrev_b32_e32 v68, 16, v147
	v_and_b32_e32 v69, 0xffff0000, v147
	global_store_dwordx4 v[234:235], v[66:69], off nt
	s_nop 1
	v_lshlrev_b32_e32 v66, 16, v148
	v_and_b32_e32 v67, 0xffff0000, v148
	v_lshlrev_b32_e32 v68, 16, v149
	v_and_b32_e32 v69, 0xffff0000, v149
	global_store_dwordx4 v[234:235], v[66:69], off offset:16 nt
	ds_write_b128 v244, v[134:137]
	ds_write_b128 v244, v[138:141] offset:8704
	ds_write_b128 v245, v[142:145] offset:34816
	ds_write_b128 v245, v[146:149] offset:45056
	s_branch .LBB2_166

.LBB9_28:
	v_lshl_add_u32 v36, s61, 6, v38
	v_mad_i64_i32 v[2:3], s[6:7], s30, v36, 0
	v_lshlrev_b32_e32 v39, 3, v35
	v_or_b32_e32 v2, v2, v39
	v_lshlrev_b64 v[14:15], 2, v[2:3]
	v_lshl_add_u64 v[10:11], s[26:27], 0, v[14:15]
	s_lshl_b32 s6, s30, 7
	s_mov_b32 s7, s15
	v_lshl_add_u64 v[22:23], s[28:29], 0, v[14:15]
	v_lshl_add_u64 v[16:17], v[10:11], 0, s[6:7]
	v_lshl_add_u64 v[40:41], v[22:23], 0, s[6:7]
	global_load_dwordx4 v[2:5], v[10:11], off offset:16
	global_load_dwordx4 v[6:9], v[10:11], off
	s_nop 0
	global_load_dwordx4 v[10:13], v[16:17], off offset:16
	global_load_dwordx4 v[18:21], v[16:17], off
	s_nop 0
	global_load_dwordx4 v[14:17], v[22:23], off offset:16
	global_load_dwordx4 v[26:29], v[22:23], off
	s_nop 0
	global_load_dwordx4 v[22:25], v[40:41], off offset:16
	global_load_dwordx4 v[30:33], v[40:41], off
	s_cmp_eq_u64 s[34:35], 0
	s_cselect_b64 s[6:7], -1, 0
	s_cmp_lt_i32 s61, 1
	s_cselect_b64 s[8:9], -1, 0
	s_or_b64 s[6:7], s[8:9], s[6:7]
	s_and_b64 vcc, exec, s[6:7]
	s_cbranch_vccnz .LBB9_30
	v_ashrrev_i32_e32 v37, 31, v36
	v_lshlrev_b64 v[36:37], 12, v[36:37]
	v_lshl_or_b32 v36, v39, 2, v36
	v_lshl_add_u64 v[40:41], s[34:35], 0, v[36:37]
	s_waitcnt vmcnt(6)
	global_store_dwordx4 v[40:41], v[6:9], off nt
	global_store_dwordx4 v[40:41], v[2:5], off offset:16 nt
	v_lshl_add_u64 v[42:43], v[40:41], 0, s[18:19]
	v_add_co_u32_e32 v40, vcc, 0x20000, v40
	v_lshl_add_u64 v[36:37], s[36:37], 0, v[36:37]
	s_nop 0
	v_addc_co_u32_e32 v41, vcc, 0, v41, vcc
	s_waitcnt vmcnt(6)
	global_store_dwordx4 v[40:41], v[18:21], off nt
	global_store_dwordx4 v[42:43], v[10:13], off offset:16 nt
	s_waitcnt vmcnt(6)
	global_store_dwordx4 v[36:37], v[26:29], off nt
	global_store_dwordx4 v[36:37], v[14:17], off offset:16 nt
	v_lshl_add_u64 v[40:41], v[36:37], 0, s[18:19]
	v_add_co_u32_e32 v36, vcc, 0x20000, v36
	s_nop 1
	v_addc_co_u32_e32 v37, vcc, 0, v37, vcc
	s_waitcnt vmcnt(6)
	global_store_dwordx4 v[36:37], v[30:33], off nt
	global_store_dwordx4 v[40:41], v[22:25], off offset:16 nt

.LBB9_49:
	s_cmp_lt_i32 s66, s43
	s_cselect_b64 s[40:41], -1, 0
	s_cmp_ge_i32 s66, s43
	s_cbranch_scc1 .LBB9_55
	s_add_i32 s14, s65, 1
	s_cmp_ge_i32 s14, s60
	s_cbranch_scc1 .LBB9_54
	v_subrev_u32_e32 v70, 64, v136
	v_mad_i64_i32 v[36:37], s[38:39], s30, v70, 0
	v_or_b32_e32 v36, v36, v134
	v_lshlrev_b64 v[48:49], 2, v[36:37]
	v_lshl_add_u64 v[44:45], s[26:27], 0, v[48:49]
	s_lshl_b32 s14, s48, 2
	v_lshl_add_u64 v[56:57], s[28:29], 0, v[48:49]
	v_lshl_add_u64 v[50:51], v[44:45], 0, s[14:15]
	v_lshl_add_u64 v[64:65], v[56:57], 0, s[14:15]
	global_load_dwordx4 v[36:39], v[44:45], off offset:16
	global_load_dwordx4 v[40:43], v[44:45], off
	s_nop 0
	global_load_dwordx4 v[44:47], v[50:51], off offset:16
	global_load_dwordx4 v[52:55], v[50:51], off
	s_nop 0
	global_load_dwordx4 v[48:51], v[56:57], off offset:16
	global_load_dwordx4 v[60:63], v[56:57], off
	s_nop 0
	global_load_dwordx4 v[56:59], v[64:65], off offset:16
	s_nop 0
	global_load_dwordx4 v[64:67], v[64:65], off
	s_cmp_lt_i32 s65, 0
	s_cselect_b64 s[38:39], -1, 0
	s_xor_b64 s[68:69], s[6:7], -1
	s_or_b64 s[38:39], s[68:69], s[38:39]
	s_and_b64 vcc, exec, s[38:39]
	s_cbranch_vccnz .LBB9_53
	v_ashrrev_i32_e32 v71, 31, v70
	v_lshlrev_b64 v[70:71], 12, v[70:71]
	v_lshl_or_b32 v70, v134, 2, v70
	s_waitcnt vmcnt(11)
	v_lshl_add_u64 v[88:89], s[34:35], 0, v[70:71]
	s_waitcnt vmcnt(6)
	global_store_dwordx4 v[88:89], v[40:43], off nt
	global_store_dwordx4 v[88:89], v[36:39], off offset:16 nt
	v_lshl_add_u64 v[90:91], v[88:89], 0, s[18:19]
	v_add_co_u32_e32 v88, vcc, 0x20000, v88
	v_lshl_add_u64 v[70:71], s[36:37], 0, v[70:71]
	s_nop 0
	v_addc_co_u32_e32 v89, vcc, 0, v89, vcc
	s_waitcnt vmcnt(6)
	global_store_dwordx4 v[88:89], v[52:55], off nt
	global_store_dwordx4 v[90:91], v[44:47], off offset:16 nt
	s_waitcnt vmcnt(6)
	global_store_dwordx4 v[70:71], v[60:63], off nt
	global_store_dwordx4 v[70:71], v[48:51], off offset:16 nt
	v_lshl_add_u64 v[88:89], v[70:71], 0, s[18:19]
	v_add_co_u32_e32 v70, vcc, 0x20000, v70
	s_nop 1
	v_addc_co_u32_e32 v71, vcc, 0, v71, vcc
	s_waitcnt vmcnt(6)
	global_store_dwordx4 v[70:71], v[64:67], off nt
	global_store_dwordx4 v[88:89], v[56:59], off offset:16 nt

.LBB9_68:
	s_andn2_b64 vcc, exec, s[10:11]
	s_cbranch_vccnz .LBB9_74
	s_add_i32 s10, s65, 2
	s_cmp_ge_i32 s10, s60
	s_cbranch_scc1 .LBB9_73
	v_mad_i64_i32 v[36:37], s[10:11], s30, v136, 0
	v_or_b32_e32 v36, v36, v134
	v_lshlrev_b64 v[48:49], 2, v[36:37]
	v_lshl_add_u64 v[44:45], s[26:27], 0, v[48:49]
	s_lshl_b32 s14, s48, 2
	v_lshl_add_u64 v[56:57], s[28:29], 0, v[48:49]
	v_lshl_add_u64 v[50:51], v[44:45], 0, s[14:15]
	v_lshl_add_u64 v[64:65], v[56:57], 0, s[14:15]
	global_load_dwordx4 v[36:39], v[44:45], off offset:16
	global_load_dwordx4 v[40:43], v[44:45], off
	s_nop 0
	global_load_dwordx4 v[44:47], v[50:51], off offset:16
	global_load_dwordx4 v[52:55], v[50:51], off
	s_nop 0
	global_load_dwordx4 v[48:51], v[56:57], off offset:16
	global_load_dwordx4 v[60:63], v[56:57], off
	s_nop 0
	global_load_dwordx4 v[56:59], v[64:65], off offset:16
	s_nop 0
	global_load_dwordx4 v[64:67], v[64:65], off
	s_cmp_lt_i32 s65, -1
	s_cselect_b64 s[10:11], -1, 0
	s_xor_b64 s[38:39], s[6:7], -1
	s_or_b64 s[10:11], s[38:39], s[10:11]
	s_and_b64 vcc, exec, s[10:11]
	s_cbranch_vccnz .LBB9_72
	v_ashrrev_i32_e32 v137, 31, v136
	v_lshlrev_b64 v[70:71], 12, v[136:137]
	v_lshl_or_b32 v70, v134, 2, v70
	s_waitcnt vmcnt(11)
	v_lshl_add_u64 v[104:105], s[34:35], 0, v[70:71]
	s_waitcnt vmcnt(6)
	global_store_dwordx4 v[104:105], v[40:43], off nt
	global_store_dwordx4 v[104:105], v[36:39], off offset:16 nt
	v_lshl_add_u64 v[106:107], v[104:105], 0, s[18:19]
	v_add_co_u32_e32 v104, vcc, 0x20000, v104
	v_lshl_add_u64 v[70:71], s[36:37], 0, v[70:71]
	s_nop 0
	v_addc_co_u32_e32 v105, vcc, 0, v105, vcc
	s_waitcnt vmcnt(6)
	global_store_dwordx4 v[104:105], v[52:55], off nt
	global_store_dwordx4 v[106:107], v[44:47], off offset:16 nt
	s_waitcnt vmcnt(6)
	global_store_dwordx4 v[70:71], v[60:63], off nt
	global_store_dwordx4 v[70:71], v[48:51], off offset:16 nt
	v_lshl_add_u64 v[104:105], v[70:71], 0, s[18:19]
	v_add_co_u32_e32 v70, vcc, 0x20000, v70
	s_nop 1
	v_addc_co_u32_e32 v71, vcc, 0, v71, vcc
	s_waitcnt vmcnt(6)
	global_store_dwordx4 v[70:71], v[64:67], off nt
	global_store_dwordx4 v[104:105], v[56:59], off offset:16 nt

.LBB9_117:
	v_lshl_add_u32 v36, s64, 6, v38
	v_mad_i64_i32 v[2:3], s[4:5], s28, v36, 0
	v_or_b32_e32 v2, v2, v130
	v_lshlrev_b64 v[14:15], 2, v[2:3]
	v_lshl_add_u64 v[10:11], s[24:25], 0, v[14:15]
	s_lshl_b32 s4, s28, 7
	s_mov_b32 s5, s13
	v_lshl_add_u64 v[22:23], s[26:27], 0, v[14:15]
	v_lshl_add_u64 v[16:17], v[10:11], 0, s[4:5]
	v_lshl_add_u64 v[30:31], v[22:23], 0, s[4:5]
	global_load_dwordx4 v[2:5], v[10:11], off offset:16
	global_load_dwordx4 v[6:9], v[10:11], off
	s_nop 0
	global_load_dwordx4 v[10:13], v[16:17], off offset:16
	global_load_dwordx4 v[18:21], v[16:17], off
	s_nop 0
	global_load_dwordx4 v[14:17], v[22:23], off offset:16
	global_load_dwordx4 v[26:29], v[22:23], off
	s_nop 0
	global_load_dwordx4 v[22:25], v[30:31], off offset:16
	s_nop 0
	global_load_dwordx4 v[30:33], v[30:31], off
	s_cmp_eq_u64 s[30:31], 0
	s_cselect_b64 s[4:5], -1, 0
	s_cmp_lt_i32 s64, 1
	s_cselect_b64 s[6:7], -1, 0
	s_or_b64 s[4:5], s[6:7], s[4:5]
	s_and_b64 vcc, exec, s[4:5]
	s_cbranch_vccnz .LBB9_119
	v_ashrrev_i32_e32 v37, 31, v36
	v_lshlrev_b64 v[36:37], 12, v[36:37]
	v_lshl_or_b32 v36, v130, 2, v36
	v_lshl_add_u64 v[40:41], s[30:31], 0, v[36:37]
	s_waitcnt vmcnt(6)
	global_store_dwordx4 v[40:41], v[6:9], off nt
	global_store_dwordx4 v[40:41], v[2:5], off offset:16 nt
	v_lshl_add_u64 v[42:43], v[40:41], 0, s[16:17]
	v_add_co_u32_e32 v40, vcc, 0x20000, v40
	v_lshl_add_u64 v[36:37], s[34:35], 0, v[36:37]
	s_nop 0
	v_addc_co_u32_e32 v41, vcc, 0, v41, vcc
	s_waitcnt vmcnt(6)
	global_store_dwordx4 v[40:41], v[18:21], off nt
	global_store_dwordx4 v[42:43], v[10:13], off offset:16 nt
	s_waitcnt vmcnt(6)
	global_store_dwordx4 v[36:37], v[26:29], off nt
	global_store_dwordx4 v[36:37], v[14:17], off offset:16 nt
	v_lshl_add_u64 v[40:41], v[36:37], 0, s[16:17]
	v_add_co_u32_e32 v36, vcc, 0x20000, v36
	s_nop 1
	v_addc_co_u32_e32 v37, vcc, 0, v37, vcc
	s_waitcnt vmcnt(6)
	global_store_dwordx4 v[36:37], v[30:33], off nt
	global_store_dwordx4 v[40:41], v[22:25], off offset:16 nt

.LBB9_138:
	s_cmp_lt_i32 s69, s41
	s_cselect_b64 s[38:39], -1, 0
	s_cmp_ge_i32 s69, s41
	s_cbranch_scc1 .LBB9_144
	s_add_i32 s12, s68, 1
	s_cmp_ge_i32 s12, s63
	s_cbranch_scc1 .LBB9_143
	v_subrev_u32_e32 v70, 64, v136
	v_mad_i64_i32 v[36:37], s[36:37], s28, v70, 0
	v_or_b32_e32 v36, v36, v130
	v_lshlrev_b64 v[48:49], 2, v[36:37]
	v_lshl_add_u64 v[44:45], s[24:25], 0, v[48:49]
	s_lshl_b32 s12, s46, 2
	v_lshl_add_u64 v[56:57], s[26:27], 0, v[48:49]
	v_lshl_add_u64 v[50:51], v[44:45], 0, s[12:13]
	v_lshl_add_u64 v[64:65], v[56:57], 0, s[12:13]
	global_load_dwordx4 v[36:39], v[44:45], off offset:16
	global_load_dwordx4 v[40:43], v[44:45], off
	s_nop 0
	global_load_dwordx4 v[44:47], v[50:51], off offset:16
	global_load_dwordx4 v[52:55], v[50:51], off
	s_nop 0
	global_load_dwordx4 v[48:51], v[56:57], off offset:16
	global_load_dwordx4 v[60:63], v[56:57], off
	s_nop 0
	global_load_dwordx4 v[56:59], v[64:65], off offset:16
	s_nop 0
	global_load_dwordx4 v[64:67], v[64:65], off
	s_cmp_lt_i32 s68, 0
	s_cselect_b64 s[36:37], -1, 0
	s_xor_b64 s[72:73], s[4:5], -1
	s_or_b64 s[36:37], s[72:73], s[36:37]
	s_and_b64 vcc, exec, s[36:37]
	s_cbranch_vccnz .LBB9_142
	v_ashrrev_i32_e32 v71, 31, v70
	v_lshlrev_b64 v[70:71], 12, v[70:71]
	v_lshl_or_b32 v70, v130, 2, v70
	s_waitcnt vmcnt(11)
	v_lshl_add_u64 v[88:89], s[30:31], 0, v[70:71]
	s_waitcnt vmcnt(6)
	global_store_dwordx4 v[88:89], v[40:43], off nt
	global_store_dwordx4 v[88:89], v[36:39], off offset:16 nt
	v_lshl_add_u64 v[90:91], v[88:89], 0, s[16:17]
	v_add_co_u32_e32 v88, vcc, 0x20000, v88
	v_lshl_add_u64 v[70:71], s[34:35], 0, v[70:71]
	s_nop 0
	v_addc_co_u32_e32 v89, vcc, 0, v89, vcc
	s_waitcnt vmcnt(6)
	global_store_dwordx4 v[88:89], v[52:55], off nt
	global_store_dwordx4 v[90:91], v[44:47], off offset:16 nt
	s_waitcnt vmcnt(6)
	global_store_dwordx4 v[70:71], v[60:63], off nt
	global_store_dwordx4 v[70:71], v[48:51], off offset:16 nt
	v_lshl_add_u64 v[88:89], v[70:71], 0, s[16:17]
	v_add_co_u32_e32 v70, vcc, 0x20000, v70
	s_nop 1
	v_addc_co_u32_e32 v71, vcc, 0, v71, vcc
	s_waitcnt vmcnt(6)
	global_store_dwordx4 v[70:71], v[64:67], off nt
	global_store_dwordx4 v[88:89], v[56:59], off offset:16 nt
	s_nop 1
	v_cvt_pk_bf16_f32 v88, v40, v41
	v_cvt_pk_bf16_f32 v89, v42, v43
	v_cvt_pk_bf16_f32 v90, v36, v37
	v_cvt_pk_bf16_f32 v91, v38, v39
	v_cvt_pk_bf16_f32 v92, v52, v53
	v_cvt_pk_bf16_f32 v93, v54, v55
	v_cvt_pk_bf16_f32 v94, v44, v45
	v_cvt_pk_bf16_f32 v95, v46, v47
	v_cvt_pk_bf16_f32 v96, v60, v61
	v_cvt_pk_bf16_f32 v97, v62, v63
	v_cvt_pk_bf16_f32 v98, v48, v49
	v_cvt_pk_bf16_f32 v99, v50, v51
	v_cvt_pk_bf16_f32 v100, v64, v65
	v_cvt_pk_bf16_f32 v101, v66, v67
	v_cvt_pk_bf16_f32 v102, v56, v57
	v_cvt_pk_bf16_f32 v103, v58, v59
	ds_write_b128 v132, v[88:91] offset:17408
	ds_write_b128 v132, v[92:95] offset:26112
	ds_write_b128 v135, v[96:99]
	ds_write_b128 v135, v[100:103] offset:10240
	s_branch .LBB9_144

.LBB9_157:
	s_andn2_b64 vcc, exec, s[8:9]
	s_cbranch_vccnz .LBB9_163
	s_add_i32 s8, s68, 2
	s_cmp_ge_i32 s8, s63
	s_cbranch_scc1 .LBB9_162
	v_mad_i64_i32 v[36:37], s[8:9], s28, v136, 0
	v_or_b32_e32 v36, v36, v130
	v_lshlrev_b64 v[48:49], 2, v[36:37]
	v_lshl_add_u64 v[44:45], s[24:25], 0, v[48:49]
	s_lshl_b32 s12, s46, 2
	v_lshl_add_u64 v[56:57], s[26:27], 0, v[48:49]
	v_lshl_add_u64 v[50:51], v[44:45], 0, s[12:13]
	v_lshl_add_u64 v[64:65], v[56:57], 0, s[12:13]
	global_load_dwordx4 v[36:39], v[44:45], off offset:16
	global_load_dwordx4 v[40:43], v[44:45], off
	s_nop 0
	global_load_dwordx4 v[44:47], v[50:51], off offset:16
	global_load_dwordx4 v[52:55], v[50:51], off
	s_nop 0
	global_load_dwordx4 v[48:51], v[56:57], off offset:16
	global_load_dwordx4 v[60:63], v[56:57], off
	s_nop 0
	global_load_dwordx4 v[56:59], v[64:65], off offset:16
	s_nop 0
	global_load_dwordx4 v[64:67], v[64:65], off
	s_cmp_lt_i32 s68, -1
	s_cselect_b64 s[8:9], -1, 0
	s_xor_b64 s[36:37], s[4:5], -1
	s_or_b64 s[8:9], s[36:37], s[8:9]
	s_and_b64 vcc, exec, s[8:9]
	s_cbranch_vccnz .LBB9_161
	v_ashrrev_i32_e32 v137, 31, v136
	v_lshlrev_b64 v[70:71], 12, v[136:137]
	v_lshl_or_b32 v70, v130, 2, v70
	s_waitcnt vmcnt(11)
	v_lshl_add_u64 v[104:105], s[30:31], 0, v[70:71]
	s_waitcnt vmcnt(6)
	global_store_dwordx4 v[104:105], v[40:43], off nt
	global_store_dwordx4 v[104:105], v[36:39], off offset:16 nt
	v_lshl_add_u64 v[106:107], v[104:105], 0, s[16:17]
	v_add_co_u32_e32 v104, vcc, 0x20000, v104
	v_lshl_add_u64 v[70:71], s[34:35], 0, v[70:71]
	s_nop 0
	v_addc_co_u32_e32 v105, vcc, 0, v105, vcc
	s_waitcnt vmcnt(6)
	global_store_dwordx4 v[104:105], v[52:55], off nt
	global_store_dwordx4 v[106:107], v[44:47], off offset:16 nt
	s_waitcnt vmcnt(6)
	global_store_dwordx4 v[70:71], v[60:63], off nt
	global_store_dwordx4 v[70:71], v[48:51], off offset:16 nt
	v_lshl_add_u64 v[104:105], v[70:71], 0, s[16:17]
	v_add_co_u32_e32 v70, vcc, 0x20000, v70
	s_nop 1
	v_addc_co_u32_e32 v71, vcc, 0, v71, vcc
	s_waitcnt vmcnt(6)
	global_store_dwordx4 v[70:71], v[64:67], off nt
	global_store_dwordx4 v[104:105], v[56:59], off offset:16 nt
	s_nop 1
	v_cvt_pk_bf16_f32 v104, v40, v41
	v_cvt_pk_bf16_f32 v105, v42, v43
	v_cvt_pk_bf16_f32 v106, v36, v37
	v_cvt_pk_bf16_f32 v107, v38, v39
	v_cvt_pk_bf16_f32 v108, v52, v53
	v_cvt_pk_bf16_f32 v109, v54, v55
	v_cvt_pk_bf16_f32 v110, v44, v45
	v_cvt_pk_bf16_f32 v111, v46, v47
	v_cvt_pk_bf16_f32 v112, v60, v61
	v_cvt_pk_bf16_f32 v113, v62, v63
	v_cvt_pk_bf16_f32 v114, v48, v49
	v_cvt_pk_bf16_f32 v115, v50, v51
	v_cvt_pk_bf16_f32 v116, v64, v65
	v_cvt_pk_bf16_f32 v117, v66, v67
	v_cvt_pk_bf16_f32 v118, v56, v57
	v_cvt_pk_bf16_f32 v119, v58, v59
	ds_write_b128 v132, v[104:107]
	ds_write_b128 v132, v[108:111] offset:8704
	ds_write_b128 v134, v[112:115] offset:34816
	ds_write_b128 v134, v[116:119] offset:45056
	s_branch .LBB9_163
